# attention loops: stage-counter / LDS-base SALU+VALU setup moved in front of the loop-top barrier (off the post-barrier critical path)
# speedup vs baseline: 1.0003x; 1.0003x over previous
.LBB0_1290:
	s_cmpk_gt_u32 s52, 0x7f
	s_cselect_b64 vcc, 0, exec
	s_mul_i32 s100, s55, 0x6000
	s_add_i32 s52, s52, 2
	s_xor_b32 s55, s55, 2
	v_add_u32_e32 v167, s100, v171
	s_waitcnt vmcnt(0) lgkmcnt(0)
	s_barrier

.LBB0_1300:
	s_cmpk_gt_u32 s52, 0x7f
	s_cselect_b64 vcc, 0, exec
	s_mul_i32 s100, s55, 0x6000
	s_add_i32 s52, s52, 2
	s_xor_b32 s55, s55, 2
	v_add_u32_e32 v179, s100, v171
	s_waitcnt vmcnt(0) lgkmcnt(0)
	s_barrier

.LBB0_4062:
	s_cmpk_gt_u32 s65, 0x7f
	s_cselect_b64 vcc, 0, exec
	s_mul_i32 s100, s67, 0x6000
	s_add_i32 s65, s65, 2
	s_xor_b32 s67, s67, 2
	v_add_u32_e32 v167, s100, v171
	s_waitcnt vmcnt(0) lgkmcnt(0)
	s_barrier

.LBB0_4072:
	s_cmpk_gt_u32 s55, 0x7f
	s_cselect_b64 vcc, 0, exec
	s_mul_i32 s100, s65, 0x6000
	s_add_i32 s55, s55, 2
	s_xor_b32 s65, s65, 2
	v_add_u32_e32 v179, s100, v171
	s_waitcnt vmcnt(0) lgkmcnt(0)
	s_barrier
